# XCD-local barriers for B->C, F->G, G->H, H->I, I->J (skip cross-XCD stage; norm rows remapped to the owning XCD) on top of qk epilogue rewrite
# speedup vs baseline: 1.0581x; 1.0105x over previous
; #define LAS __attribute__((address_space(3)))
; DI unsigned xb_ld(unsigned* p)              { return __hip_atomic_load(p, __ATOMIC_RELAXED, __HIP_MEMORY_SCOPE_AGENT); }
; DI void xcd_barrier_complete(unsigned* bar, unsigned x, unsigned& nloc, unsigned& nx) {
;   const unsigned G = gridDim.x * gridDim.y * gridDim.z;
;   unsigned sum, cnt, mine, sp = 0u;
;   for (;;) {
;     sum = 0u; cnt = 0u; mine = 0u;
; #pragma unroll
;     for (unsigned j = 0; j < 16; ++j) { const unsigned c = xb_ld(&bar[XB_XCNT(j)]); sum += c; cnt += (c > 0u) ? 1u : 0u; mine = (j == x) ? c : mine; }
;     if (sum == G) break;
;     __builtin_amdgcn_s_sleep(1);
;     if ((++sp & 255u) == 0u) { if (xb_ld(&bar[XB_TMO])) break; if (sp > XB_SPIN_CAP) { atomicAdd(&bar[XB_TMO], 1u); break; } }
;   }
;   nloc = mine > 0u ? mine : 1u; nx = cnt > 0u ? cnt : 1u;
; }
; __global__ void __launch_bounds__(256, 2) fwd_megakernel(Params p) {
;     ...
;   char* ws = p.ws;
;   if (ws == nullptr) { cg::grid_group grid = cg::this_grid(); grid.sync(); }
;   if (threadIdx.x == 0) xb_words = make_uint4(0u, 0u, 0u, 0u);
;   __syncthreads();
;   const XcdBarrier xb = xcd_barrier_post((unsigned*)(ws + O_BAR), (volatile LAS unsigned*)&xb_words);
;   const int G = gridDim.x, bid = blockIdx.x;
;   const float* ADA = (const float*)(ws + O_ADA);
;   float* X = (float*)(ws + O_X);
.LBB0_19:
	s_or_b64 exec, exec, s[2:3]
	s_add_u32 s2, s0, 0xc0
	s_addc_u32 s3, s1, 0
	v_writelane_b32 v246, s2, 35
	s_load_dword s66, s[0:1], 0xc0
	s_add_u32 s0, s82, 0x1f48000
	v_writelane_b32 v246, s3, 36
	s_addc_u32 s1, s83, 0
	v_writelane_b32 v246, s0, 37
	s_add_u32 s84, s82, 0x2378000
	s_addc_u32 s85, s83, 0
	v_writelane_b32 v246, s1, 38
	v_mov_b32_e32 v217, 0x3e91f4c4
	v_readlane_b32 s2, v246, 0
	s_cmpk_lt_i32 s2, 0xd6a
	s_cselect_b64 s[0:1], -1, 0
	v_writelane_b32 v246, s0, 39
	v_mbcnt_lo_u32_b32 v0, -1, 0
	v_mov_b32_e32 v1, 0
	v_writelane_b32 v246, s1, 40
	s_add_u32 s0, s82, 0x1f78000
	s_addc_u32 s1, s83, 0
	v_writelane_b32 v246, s0, 41
	v_mov_b32_e32 v218, 0x3c0881c4
	v_mov_b32_e32 v219, 0xbab64f3b
	v_writelane_b32 v246, s1, 42
	s_add_u32 s0, s82, 0x2178000
	s_addc_u32 s1, s83, 0
	v_writelane_b32 v246, s0, 43
	v_mov_b32_e32 v220, 0x12000
	v_mov_b32_e32 v221, 0x12004
	v_writelane_b32 v246, s1, 44
	s_add_u32 s0, s82, 0x1f44000
	s_addc_u32 s1, s83, 0
	v_writelane_b32 v246, s0, 45
	v_mov_b32_e32 v222, 1
	v_mov_b32_e32 v223, 0x358637bd
	v_writelane_b32 v246, s1, 46
	s_add_u32 s0, s82, 0x1f40000
	s_addc_u32 s1, s83, 0
	v_writelane_b32 v246, s0, 47
	v_mov_b32_e32 v224, 0x12010
	v_mov_b32_e32 v185, 0xbfb8aa3b
	v_writelane_b32 v246, s1, 48
	s_add_u32 s0, s82, 0x1ec0000
	s_addc_u32 s1, s83, 0
	v_writelane_b32 v246, s0, 49
	v_mov_b32_e32 v225, 0x461c4000
	v_mov_b32_e32 v183, 0x3f2aaaaa
	v_writelane_b32 v246, s1, 50
	s_add_u32 s0, s82, 0x1e40000
	s_addc_u32 s1, s83, 0
	v_writelane_b32 v246, s0, 51
	v_mov_b32_e32 v226, 0x37000000
	v_mov_b32_e32 v227, 0x7f800000
	v_writelane_b32 v246, s1, 52
	s_add_u32 s0, s82, 0x18c0000
	s_addc_u32 s1, s83, 0
	v_writelane_b32 v246, s0, 53
	v_not_b32_e32 v228, 63
	v_not_b32_e32 v229, 31
	v_writelane_b32 v246, s1, 54
	s_add_u32 s0, s82, 0xdc0000
	s_addc_u32 s1, s83, 0
	v_writelane_b32 v246, s0, 55
	v_mov_b32_e32 v230, 0x7fc00000
	v_mbcnt_hi_u32_b32 v231, -1, v0
	v_writelane_b32 v246, s1, 56
	s_add_u32 s0, s82, 0xbc0000
	s_addc_u32 s1, s83, 0
	v_writelane_b32 v246, s0, 57
	v_mov_b32_e32 v232, 0xf149f2ca
	v_bfrev_b32_e32 v233, 1
	v_writelane_b32 v246, s1, 58
	s_add_u32 s0, s82, 0xac0000
	s_addc_u32 s1, s83, 0
	v_writelane_b32 v246, s0, 59
	v_mov_b32_e32 v234, 0xff800000
	v_mov_b32_e32 v235, 0x9000
	v_writelane_b32 v246, s1, 60
	s_add_u32 s0, s82, 0x9c0000
	s_addc_u32 s1, s83, 0
	v_writelane_b32 v246, s0, 61
	s_movk_i32 s30, 0x1f8
	s_movk_i32 s31, 0x80
	v_writelane_b32 v246, s1, 62
	s_add_u32 s0, s82, 0x13d88200
	s_addc_u32 s1, s83, 0
	s_add_u32 s64, s82, 0x13d88400
	v_writelane_b32 v246, s0, 63
	s_addc_u32 s65, s83, 0
	v_readlane_b32 s36, v246, 17
	v_writelane_b32 v245, s1, 0
	s_add_u32 s0, s82, 0x13d88500
	s_addc_u32 s1, s83, 0
	v_writelane_b32 v245, s0, 1
	v_readlane_b32 s38, v246, 19
	v_readlane_b32 s39, v246, 20
	v_writelane_b32 v245, s1, 2
	s_add_u32 s0, s82, 0x13d88600
	s_addc_u32 s1, s83, 0
	v_writelane_b32 v245, s0, 3
	v_readlane_b32 s50, v246, 31
	v_readlane_b32 s51, v246, 32
	v_writelane_b32 v245, s1, 4
	s_add_u32 s0, s82, 0x13d88700
	s_addc_u32 s1, s83, 0
	v_writelane_b32 v245, s0, 5
	v_readlane_b32 s37, v246, 18
	v_readlane_b32 s40, v246, 21
	v_writelane_b32 v245, s1, 6
	s_add_u32 s0, s82, 0x13d88800
	s_addc_u32 s1, s83, 0
	v_writelane_b32 v245, s0, 7
	v_readlane_b32 s41, v246, 22
	s_mov_b32 s40, 0x800000
	v_writelane_b32 v245, s1, 8
	s_add_u32 s0, s82, 0x13d88900
	s_addc_u32 s1, s83, 0
	v_writelane_b32 v245, s0, 9
	s_mov_b32 s34, 0x10000
	s_mov_b32 s35, 0x20000
	v_writelane_b32 v245, s1, 10
	s_add_u32 s0, s82, 0x13d88a00
	s_addc_u32 s1, s83, 0
	v_writelane_b32 v245, s0, 11
	s_mov_b32 s17, 0x30000
	s_mov_b32 s41, 0x40000
	v_writelane_b32 v245, s1, 12
	s_add_u32 s0, s82, 0x13d88b00
	s_addc_u32 s1, s83, 0
	v_writelane_b32 v245, s0, 13
	s_mov_b32 s15, 0x60000
	s_mov_b32 s87, 0x6378000
	v_writelane_b32 v245, s1, 14
	s_add_u32 s0, s82, 0x13d88c00
	s_addc_u32 s1, s83, 0
	v_writelane_b32 v245, s0, 15
	s_mov_b32 s3, 0x6398000
	s_mov_b32 s88, 0x63a8000
	v_writelane_b32 v245, s1, 16
	s_add_u32 s0, s82, 0x13d88d00
	s_addc_u32 s1, s83, 0
	v_writelane_b32 v245, s0, 17
	s_mov_b32 s89, 0x63b8000
	s_mov_b32 s86, 0x63e8000
	v_writelane_b32 v245, s1, 18
	s_add_u32 s0, s82, 0x13d88e00
	s_addc_u32 s1, s83, 0
	v_writelane_b32 v245, s0, 19
	s_mov_b32 s33, 0x1f78000
	s_mov_b32 s22, 0x2178000
	v_writelane_b32 v245, s1, 20
	s_add_u32 s0, s82, 0x13d88f00
	s_addc_u32 s1, s83, 0
	v_writelane_b32 v245, s0, 21
	s_mov_b32 s23, 0x41000000
	s_mov_b32 s14, 0xefa18f08
	v_writelane_b32 v245, s1, 22
	s_add_u32 s0, s82, 0x13d89000
	s_addc_u32 s1, s83, 0
	v_writelane_b32 v245, s0, 23
	s_movk_i32 s19, 0xfdff
	s_mov_b32 s60, 0
	v_writelane_b32 v245, s1, 24
	s_add_u32 s0, s82, 0x13d89100
	s_addc_u32 s1, s83, 0
	v_writelane_b32 v245, s0, 25
	s_mov_b64 s[12:13], 0x1f78000
	s_mov_b32 s91, 0
	v_writelane_b32 v245, s1, 26
	s_add_u32 s0, s82, 0x13d89200
	s_addc_u32 s1, s83, 0
	v_writelane_b32 v245, s0, 27
	s_mov_b32 s18, 0x3fb8aa3b
	s_mov_b32 s16, 0x3e000000
	v_writelane_b32 v245, s1, 28
	s_add_u32 s0, s82, 0x13d89300
	s_addc_u32 s1, s83, 0
	v_writelane_b32 v245, s0, 29
	s_cmp_eq_u32 s9, 15
	s_mov_b64 s[10:11], 0x100
	v_writelane_b32 v245, s1, 30
	s_cselect_b64 s[0:1], -1, 0
	v_writelane_b32 v245, s0, 31
	s_cmp_eq_u32 s9, 14
	s_mov_b64 s[92:93], 0x20000
	v_writelane_b32 v245, s1, 32
	s_cselect_b64 s[0:1], -1, 0
	v_writelane_b32 v245, s0, 33
	s_cmp_eq_u32 s9, 13
	s_mov_b64 s[94:95], 0x4000
	v_writelane_b32 v245, s1, 34
	s_cselect_b64 s[0:1], -1, 0
	v_writelane_b32 v245, s0, 35
	s_cmp_eq_u32 s9, 12
	s_mov_b64 s[96:97], 0x8000
	v_writelane_b32 v245, s1, 36
	s_cselect_b64 s[0:1], -1, 0
	v_writelane_b32 v245, s0, 37
	s_cmp_eq_u32 s9, 11
; DI unsigned xb_ld(unsigned* p)              { return __hip_atomic_load(p, __ATOMIC_RELAXED, __HIP_MEMORY_SCOPE_AGENT); }
; DI unsigned xb_add(unsigned* p, unsigned v) { return __hip_atomic_fetch_add(p, v, __ATOMIC_RELAXED, __HIP_MEMORY_SCOPE_AGENT); }
; DI void xcd_barrier_complete(unsigned* bar, unsigned x, unsigned& nloc, unsigned& nx) {
;   const unsigned G = gridDim.x * gridDim.y * gridDim.z;
;   unsigned sum, cnt, mine, sp = 0u;
;   for (;;) {
;     sum = 0u; cnt = 0u; mine = 0u;
; #pragma unroll
;     for (unsigned j = 0; j < 16; ++j) { const unsigned c = xb_ld(&bar[XB_XCNT(j)]); sum += c; cnt += (c > 0u) ? 1u : 0u; mine = (j == x) ? c : mine; }
;     if (sum == G) break;
;     __builtin_amdgcn_s_sleep(1);
;     if ((++sp & 255u) == 0u) { if (xb_ld(&bar[XB_TMO])) break; if (sp > XB_SPIN_CAP) { atomicAdd(&bar[XB_TMO], 1u); break; } }
;   }
;   nloc = mine > 0u ? mine : 1u; nx = cnt > 0u ? cnt : 1u;
; }
; DI void xcd_barrier(const XcdBarrier& b) {
;   asm volatile("s_waitcnt vmcnt(0)" ::: "memory");
;   __syncthreads();
;   if (threadIdx.x == 0) {
;     unsigned* bar = b.bar;
;     __builtin_amdgcn_s_waitcnt(0);
;     unsigned nloc = b.st[0], nx = b.st[1];
;     if (nloc == 0u) { xcd_barrier_complete(bar, b.x, nloc, nx); b.st[0] = nloc; b.st[1] = nx; }
;     const unsigned old = xb_add(&bar[XB_XSUB(b.x)], 1u);
;     const unsigned gen = old / nloc;
;     if (old + 1u == (gen + 1u) * nloc) {
;       __builtin_amdgcn_fence(__ATOMIC_RELEASE, "agent");
;       asm volatile("s_waitcnt vmcnt(0)" ::: "memory");
;       const unsigned og = xb_add(&bar[XB_TOP], 1u);
;       const unsigned tg = og / nx;
;       if (og + 1u == (tg + 1u) * nx) xb_add(&bar[XB_TOPGEN], 1u);
	s_mov_b64 s[20:21], s[36:37]
	v_writelane_b32 v245, s1, 38
	s_cselect_b64 s[0:1], -1, 0
	v_writelane_b32 v245, s0, 39
	s_cmp_eq_u32 s9, 10
	v_readlane_b32 s42, v246, 23
	v_writelane_b32 v245, s1, 40
	s_cselect_b64 s[0:1], -1, 0
	v_writelane_b32 v245, s0, 41
	s_cmp_eq_u32 s9, 9
	v_readlane_b32 s43, v246, 24
	v_writelane_b32 v245, s1, 42
	s_cselect_b64 s[0:1], -1, 0
	v_writelane_b32 v245, s0, 43
	s_cmp_eq_u32 s9, 8
	v_readlane_b32 s44, v246, 25
	v_writelane_b32 v245, s1, 44
	s_cselect_b64 s[0:1], -1, 0
	v_writelane_b32 v245, s0, 45
	s_cmp_eq_u32 s9, 7
	v_readlane_b32 s45, v246, 26
	v_writelane_b32 v245, s1, 46
	s_cselect_b64 s[0:1], -1, 0
	v_writelane_b32 v245, s0, 47
	s_cmp_eq_u32 s9, 6
	v_readlane_b32 s46, v246, 27
	v_writelane_b32 v245, s1, 48
	s_cselect_b64 s[0:1], -1, 0
	v_writelane_b32 v245, s0, 49
	s_cmp_eq_u32 s9, 5
	v_readlane_b32 s47, v246, 28
	v_writelane_b32 v245, s1, 50
	s_cselect_b64 s[0:1], -1, 0
	v_writelane_b32 v245, s0, 51
	s_cmp_eq_u32 s9, 4
	v_readlane_b32 s48, v246, 29
	v_writelane_b32 v245, s1, 52
	s_cselect_b64 s[0:1], -1, 0
	v_writelane_b32 v245, s0, 53
	s_cmp_eq_u32 s9, 3
	v_readlane_b32 s49, v246, 30
	v_writelane_b32 v245, s1, 54
	s_cselect_b64 s[0:1], -1, 0
	v_writelane_b32 v245, s0, 55
	s_cmp_eq_u32 s9, 2
	s_nop 0
	v_writelane_b32 v245, s1, 56
	s_cselect_b64 s[0:1], -1, 0
	v_writelane_b32 v245, s0, 57
	s_cmp_eq_u32 s9, 1
	s_nop 0
	v_writelane_b32 v245, s1, 58
	s_cselect_b64 s[0:1], -1, 0
	v_writelane_b32 v245, s0, 59
	s_cmp_eq_u32 s9, 0
	s_nop 0
	v_writelane_b32 v245, s1, 60
	s_cselect_b64 s[0:1], -1, 0
	v_writelane_b32 v245, s0, 61
	s_nop 1
	v_writelane_b32 v245, s1, 62
	s_lshl_b32 s0, s8, 2
	s_add_u32 s0, s6, s0
	s_addc_u32 s1, s7, 0
	s_add_u32 s4, s0, 0x1400
	s_addc_u32 s5, s1, 0
	s_add_u32 s0, s0, 0x2400
	v_writelane_b32 v245, s4, 63
	s_addc_u32 s1, s1, 0
	s_movk_i32 s8, 0x210
	v_writelane_b32 v244, s5, 0
	v_writelane_b32 v244, s0, 1
	s_mov_b64 s[6:7], 0x2178000
	s_nop 0
	v_writelane_b32 v244, s1, 2
	s_add_u32 s0, s82, 0x13d8b400
	s_addc_u32 s1, s83, 0
	v_writelane_b32 v244, s0, 3
	s_nop 1
	v_writelane_b32 v244, s1, 4
	s_add_u32 s0, s82, 0x13d8b500
	s_addc_u32 s1, s83, 0
	v_writelane_b32 v244, s0, 5
	s_nop 1
	v_writelane_b32 v244, s1, 6
	s_add_u32 s0, s82, 0x6378000
	s_addc_u32 s1, s83, 0
	v_writelane_b32 v244, s0, 7
	s_waitcnt lgkmcnt(0)
; DI int otid() { int t = threadIdx.x; asm volatile("" : "+v"(t)); return t; }
; DI void norm_rows(const float* __restrict__ xin, const float* __restrict__ gn, const float* __restrict__ ada_sh, const float* __restrict__ ada_sc,
;                   bf16_t* __restrict__ H) {
;   const int tid_ = otid(), lane = tid_ & 63, w = tid_ >> 6;
;   const int nw = gridDim.x * 4;
;   for (int row0 = (blockIdx.x * 4 + w) * 8; row0 < T; row0 += nw * 8) {
	s_lshl_b32 s4, s66, 5
	v_writelane_b32 v244, s1, 8
	s_and_b32 s0, s2, 7
	s_lshl_b32 s0, s0, 6
	s_lshr_b32 s98, s2, 3
	s_or_b32 s0, s0, s98
	s_lshl_b32 s0, s0, 5
	s_cmpk_lt_i32 s2, 0xa00
	v_writelane_b32 v244, s0, 9
	s_cselect_b64 s[0:1], -1, 0
	v_writelane_b32 v244, s0, 10
	s_nop 1
	v_writelane_b32 v244, s1, 11
	s_add_u32 s0, s82, 0xa778000
	v_writelane_b32 v244, s0, 12
	s_addc_u32 s0, s83, 0
	v_writelane_b32 v244, s0, 13
	s_add_u32 s0, s82, 0x9f78000
	v_writelane_b32 v244, s0, 14
	s_addc_u32 s0, s83, 0
	v_writelane_b32 v244, s0, 15
	s_add_u32 s0, s82, 0xa378000
	v_writelane_b32 v244, s0, 16
	s_addc_u32 s0, s83, 0
	v_writelane_b32 v244, s0, 17
	s_add_u32 s0, s82, 0x9b78000
	v_writelane_b32 v244, s0, 18
	s_addc_u32 s0, s83, 0
	v_writelane_b32 v244, s0, 19
	s_add_u32 s0, s82, 0x11b78000
	s_addc_u32 s1, s83, 0
	v_writelane_b32 v244, s0, 20
	s_nop 1
	v_writelane_b32 v244, s1, 21
	s_add_u32 s0, s82, 0xcb78000
	v_writelane_b32 v244, s0, 22
	s_addc_u32 s0, s83, 0
	v_writelane_b32 v244, s0, 23
	s_add_u32 s0, s82, 0x8378000
	s_addc_u32 s1, s83, 0
	v_writelane_b32 v244, s0, 24
	s_cmpk_lt_i32 s2, 0x180
	s_nop 0
	v_writelane_b32 v244, s1, 25
	s_cselect_b64 s[0:1], -1, 0
	v_writelane_b32 v244, s0, 26
	s_nop 1
	v_writelane_b32 v244, s1, 27
	s_add_u32 s0, s82, 0xbb78000
	v_writelane_b32 v244, s0, 28
	s_addc_u32 s0, s83, 0
	v_writelane_b32 v244, s0, 29
	s_add_u32 s0, s82, 0x11d78000
	s_addc_u32 s1, s83, 0
	v_writelane_b32 v244, s0, 30
	s_nop 1
	v_writelane_b32 v244, s1, 31
	s_add_u32 s0, s82, 0x11d38000
	s_addc_u32 s1, s83, 0
	v_writelane_b32 v244, s0, 32
	s_nop 1
	v_writelane_b32 v244, s1, 33
	s_add_u32 s0, s82, 0x11cf8000
	s_addc_u32 s1, s83, 0
	v_writelane_b32 v244, s0, 34
	s_nop 1
	v_writelane_b32 v244, s1, 35
	s_add_u32 s0, s82, 0x13d8b800
	v_writelane_b32 v244, s0, 36
	s_addc_u32 s0, s83, 0
	v_writelane_b32 v244, s0, 37
	s_add_u32 s0, s82, 0xab78000
	s_addc_u32 s1, s83, 0
	v_writelane_b32 v244, s0, 38
	s_nop 1
	v_writelane_b32 v244, s1, 39
	s_add_u32 s0, s82, 0x12d88000
	s_addc_u32 s1, s83, 0
	v_writelane_b32 v244, s0, 40
	s_nop 1
	v_writelane_b32 v244, s1, 41
	s_add_u32 s0, s82, 0x11d88000
	s_addc_u32 s1, s83, 0
	v_writelane_b32 v244, s0, 42
	s_cmpk_lt_i32 s2, 0x200
	s_nop 0
	v_writelane_b32 v244, s1, 43
	s_cselect_b64 s[0:1], -1, 0
	v_writelane_b32 v244, s0, 44
	s_cmpk_lt_i32 s2, 0xc00
	s_nop 0
	v_writelane_b32 v244, s1, 45
	s_cselect_b64 s[0:1], -1, 0
	v_writelane_b32 v244, s0, 46
	s_nop 1
	v_writelane_b32 v244, s1, 47
	s_add_u32 s0, s82, 0x637be04
	s_addc_u32 s1, s83, 0
	v_writelane_b32 v244, s0, 48
	s_ashr_i32 s5, s4, 31
	s_lshl_b32 s67, s66, 3
	v_writelane_b32 v244, s1, 49
	s_lshl_b32 s0, s2, 3
	v_writelane_b32 v244, s0, 50
	s_lshl_b64 s[0:1], s[4:5], 11
	v_writelane_b32 v244, s0, 51
	s_nop 1
	v_writelane_b32 v244, s1, 52
	s_mov_b32 s0, s4
	v_writelane_b32 v244, s0, 53
	s_nop 1
	v_writelane_b32 v244, s1, 54
	s_lshl_b64 s[0:1], s[4:5], 12
	v_writelane_b32 v244, s0, 55
	s_mov_b32 s4, 0x63c8000
	s_mov_b32 s5, 0x63d8000
	v_writelane_b32 v244, s1, 56
	s_add_u32 s0, s82, 0xa778010
	s_addc_u32 s1, s83, 0
	v_writelane_b32 v244, s0, 57
	s_nop 1
	v_writelane_b32 v244, s1, 58
	s_add_u32 s0, s38, 0x80
	s_addc_u32 s1, s39, 0
	v_writelane_b32 v244, s0, 59
	s_mov_b64 s[38:39], 0x10000
	s_nop 0
	v_writelane_b32 v244, s1, 60
	s_add_u32 s0, s82, 0xa378010
	s_addc_u32 s1, s83, 0
	v_writelane_b32 v244, s0, 61
	s_nop 1
	v_writelane_b32 v244, s1, 62
	s_add_u32 s0, s82, 0x977801c
	s_addc_u32 s1, s83, 0
	v_writelane_b32 v244, s0, 63
	s_nop 1
	v_writelane_b32 v243, s1, 0
	s_add_u32 s0, s82, 0x937801c
	s_addc_u32 s1, s83, 0
	v_writelane_b32 v243, s0, 1
	s_nop 1
	v_writelane_b32 v243, s1, 2
	s_add_u32 s0, s82, 0xdb76a10
	s_addc_u32 s1, s83, 0
	v_writelane_b32 v243, s0, 3
	s_nop 1
	v_writelane_b32 v243, s1, 4
	s_add_u32 s0, s82, 0xcb78010
	s_addc_u32 s1, s83, 0
	v_writelane_b32 v243, s0, 5
	s_nop 1
	v_writelane_b32 v243, s1, 6
	s_add_u32 s0, s82, 0xbb77240
	s_addc_u32 s1, s83, 0
	v_writelane_b32 v243, s0, 7
	s_nop 1
	v_writelane_b32 v243, s1, 8
	s_add_u32 s0, s82, 0xab77640
	s_addc_u32 s1, s83, 0
	v_writelane_b32 v243, s0, 9
	s_nop 1
	v_writelane_b32 v243, s1, 10
	s_add_u32 s0, s82, 0x8378040
	s_addc_u32 s1, s83, 0
	v_writelane_b32 v243, s0, 11
	s_nop 1
	v_writelane_b32 v243, s1, 12
	s_lshl_b32 s0, s2, 7
	s_addk_i32 s0, 0xc000
	v_writelane_b32 v243, s0, 13
	s_add_i32 s0, s2, 0xffffff80
	v_writelane_b32 v243, s0, 14
	s_lshl_b32 s0, s66, 7
	v_writelane_b32 v243, s0, 15
	s_lshl_b32 s0, s2, 2
	v_writelane_b32 v243, s0, 16
	s_lshl_b32 s0, s66, 2
	v_writelane_b32 v243, s0, 17
	s_add_u32 s0, s82, 0xdb78000
	s_addc_u32 s1, s83, 0
	v_writelane_b32 v243, s0, 18
	s_mov_b32 s2, 0x6388000
	s_nop 0
	v_writelane_b32 v243, s1, 19
	s_add_u32 s0, s82, 0xdb78800
	s_addc_u32 s1, s83, 0
	v_writelane_b32 v243, s0, 20
	s_nop 1
	v_writelane_b32 v243, s1, 21
	s_mov_b64 s[0:1], s[50:51]
	v_writelane_b32 v243, s0, 22
	s_nop 1
	v_writelane_b32 v243, s1, 23
	v_writelane_b32 v243, s64, 24
	s_mov_b64 s[0:1], s[68:69]
	s_nop 0
	v_writelane_b32 v243, s65, 25
	v_writelane_b32 v243, s67, 26
	s_branch .LBB0_23

; DI unsigned xb_ld(unsigned* p)              { return __hip_atomic_load(p, __ATOMIC_RELAXED, __HIP_MEMORY_SCOPE_AGENT); }
; DI unsigned xb_add(unsigned* p, unsigned v) { return __hip_atomic_fetch_add(p, v, __ATOMIC_RELAXED, __HIP_MEMORY_SCOPE_AGENT); }
; #define XB_SPIN(cond, bar) do { unsigned _sp = 0; while (cond) { __builtin_amdgcn_s_sleep(1); \
;     if ((++_sp & 255u) == 0u) { if (xb_ld(&(bar)[XB_TMO])) break; if (_sp > XB_SPIN_CAP) { atomicAdd(&(bar)[XB_TMO], 1u); break; } } } } while (0)
; DI void xcd_barrier(const XcdBarrier& b) {
;     ...
;     const unsigned old = xb_add(&bar[XB_XSUB(b.x)], 1u);
;     const unsigned gen = old / nloc;
;     if (old + 1u == (gen + 1u) * nloc) {
;       __builtin_amdgcn_fence(__ATOMIC_RELEASE, "agent");
;       asm volatile("s_waitcnt vmcnt(0)" ::: "memory");
;       const unsigned og = xb_add(&bar[XB_TOP], 1u);
;       const unsigned tg = og / nx;
;       if (og + 1u == (tg + 1u) * nx) xb_add(&bar[XB_TOPGEN], 1u);
;       else XB_SPIN(xb_ld(&bar[XB_TOPGEN]) == tg, bar);
;       __builtin_amdgcn_fence(__ATOMIC_ACQUIRE, "agent");
;       xb_add(&bar[XB_XGEN(b.x)], 1u);
;       asm volatile("s_waitcnt vmcnt(0)" ::: "memory");
.LBB0_307:
	s_andn2_saveexec_b64 s[26:27], s[26:27]
	s_cbranch_execz .LBB0_327
	s_mov_b64 s[26:27], exec
	buffer_wbl2 sc1
	s_waitcnt lgkmcnt(0)
	s_waitcnt vmcnt(0)
	s_branch .LBB0_324
	v_mbcnt_lo_u32_b32 v0, s26, 0
	v_mbcnt_hi_u32_b32 v0, s27, v0
	v_cmp_eq_u32_e32 vcc, 0, v0
	s_and_saveexec_b64 s[28:29], vcc
	s_cbranch_execz .LBB0_310
	s_bcnt1_i32_b64 s9, s[26:27]
	v_readlane_b32 s26, v244, 3
	v_mov_b32_e32 v3, s9
	v_readlane_b32 s27, v244, 4
	s_nop 4
	global_atomic_add v3, v1, v3, s[26:27] sc0

; DI unsigned xb_ld(unsigned* p)              { return __hip_atomic_load(p, __ATOMIC_RELAXED, __HIP_MEMORY_SCOPE_AGENT); }
; DI unsigned xb_add(unsigned* p, unsigned v) { return __hip_atomic_fetch_add(p, v, __ATOMIC_RELAXED, __HIP_MEMORY_SCOPE_AGENT); }
; #define XB_SPIN(cond, bar) do { unsigned _sp = 0; while (cond) { __builtin_amdgcn_s_sleep(1); \
;     if ((++_sp & 255u) == 0u) { if (xb_ld(&(bar)[XB_TMO])) break; if (_sp > XB_SPIN_CAP) { atomicAdd(&(bar)[XB_TMO], 1u); break; } } } } while (0)
; DI void xcd_barrier(const XcdBarrier& b) {
;     ...
;     const unsigned old = xb_add(&bar[XB_XSUB(b.x)], 1u);
;     const unsigned gen = old / nloc;
;     if (old + 1u == (gen + 1u) * nloc) {
;       __builtin_amdgcn_fence(__ATOMIC_RELEASE, "agent");
;       asm volatile("s_waitcnt vmcnt(0)" ::: "memory");
;       const unsigned og = xb_add(&bar[XB_TOP], 1u);
;       const unsigned tg = og / nx;
;       if (og + 1u == (tg + 1u) * nx) xb_add(&bar[XB_TOPGEN], 1u);
;       else XB_SPIN(xb_ld(&bar[XB_TOPGEN]) == tg, bar);
;       __builtin_amdgcn_fence(__ATOMIC_ACQUIRE, "agent");
;       xb_add(&bar[XB_XGEN(b.x)], 1u);
;       asm volatile("s_waitcnt vmcnt(0)" ::: "memory");
.LBB0_1160:
	s_andn2_saveexec_b64 s[24:25], s[24:25]
	s_cbranch_execz .LBB0_1180
	s_mov_b64 s[24:25], exec
	buffer_wbl2 sc1
	s_waitcnt lgkmcnt(0)
	s_waitcnt vmcnt(0)
	s_branch .LBB0_1177
	v_mbcnt_lo_u32_b32 v0, s24, 0
	v_mbcnt_hi_u32_b32 v0, s25, v0
	v_cmp_eq_u32_e32 vcc, 0, v0
	s_and_saveexec_b64 s[26:27], vcc
	s_cbranch_execz .LBB0_1163
	s_bcnt1_i32_b64 s9, s[24:25]
	v_readlane_b32 s24, v244, 3
	v_mov_b32_e32 v3, s9
	v_readlane_b32 s25, v244, 4
	s_nop 4
	global_atomic_add v3, v1, v3, s[24:25] sc0
